# baseline (speedup 1.0000x reference)
; __device__ __forceinline__ unsigned cvt_pk_bf16(float lo, float hi) { unsigned r; asm volatile("v_cvt_pk_bf16_f32 %0, %1, %2" : "=v"(r) : "v"(lo), "v"(hi)); return r; }
;     __device__ __forceinline__ void operator()(const f32x4 (&acc)[2][2][4][2], const Unit& u, int wr, int wc, int fr, int fq) const {
;     ...
;         for (int ai = 0; ai < 2; ++ai)
; #pragma unroll
;             for (int m = 0; m < 4; ++m) {
;                 const int r = r0 + ai * HALF + m * 16;
;                 const bool valid = r < NREAL + NMETA;
;                 float ssum = 0.f;
; #pragma unroll
;                 for (int bj = 0; bj < 2; ++bj) {
;                     const u32x4 hv = hold[ai][m][bj];
;                     f32x4 h0 = {__uint_as_float(hv.x << 16), __uint_as_float(hv.x & 0xffff0000u), __uint_as_float(hv.y << 16), __uint_as_float(hv.y & 0xffff0000u)};
;                     f32x4 h1 = {__uint_as_float(hv.z << 16), __uint_as_float(hv.z & 0xffff0000u), __uint_as_float(hv.w << 16), __uint_as_float(hv.w & 0xffff0000u)};
;                     h0 += acc[ai][bj][m][0]; h1 += acc[ai][bj][m][1];
;                     const int col0 = c0 + bj * HALF;
;                     u32x4 w; w.x = cvt_pk_bf16(h0[0], h0[1]); w.y = cvt_pk_bf16(h0[2], h0[3]); w.z = cvt_pk_bf16(h1[0], h1[1]); w.w = cvt_pk_bf16(h1[2], h1[3]);
;                     if (valid) *(u32x4*)(HB + (size_t)r * 2048 + col0) = w;
;                     h0 = (f32x4){__uint_as_float(w.x << 16), __uint_as_float(w.x & 0xffff0000u), __uint_as_float(w.y << 16), __uint_as_float(w.y & 0xffff0000u)};
;                     h1 = (f32x4){__uint_as_float(w.z << 16), __uint_as_float(w.z & 0xffff0000u), __uint_as_float(w.w << 16), __uint_as_float(w.w & 0xffff0000u)};
; #pragma unroll
;                     for (int j = 0; j < 4; ++j) ssum += h0[j] * h0[j] + h1[j] * h1[j];
;                 }
;                 ssum += __shfl_xor(ssum, 16); ssum += __shfl_xor(ssum, 32);
;                 if (fq == 0 && valid) atomicAdd(ssn + r, (unsigned long long)(ssum * 16777216.f));
.LBB0_208:
	v_cmp_gt_i32_e32 vcc, s84, v202
	s_waitcnt vmcnt(15)
	v_lshlrev_b32_e32 v244, 16, v228
	v_and_b32_e32 v245, 0xffff0000, v228
	v_lshlrev_b32_e32 v228, 16, v229
	v_and_b32_e32 v229, 0xffff0000, v229
	v_lshlrev_b32_e32 v246, 16, v230
	v_and_b32_e32 v247, 0xffff0000, v230
	v_lshlrev_b32_e32 v230, 16, v231
	v_and_b32_e32 v231, 0xffff0000, v231
	v_pk_add_f32 v[148:149], v[148:149], v[244:245]
	v_pk_add_f32 v[150:151], v[150:151], v[228:229]
	v_pk_add_f32 v[228:229], v[146:147], v[230:231]
	v_pk_add_f32 v[146:147], v[144:145], v[246:247]
	v_cvt_pk_bf16_f32 v144, v148, v149
	v_lshl_add_u64 v[148:149], v[200:201], 1, v[242:243]
	v_cvt_pk_bf16_f32 v145, v150, v151
	v_cvt_pk_bf16_f32 v146, v146, v147
	v_cvt_pk_bf16_f32 v147, v228, v229
	s_and_saveexec_b64 s[8:9], vcc
	s_cbranch_execz .LBB0_210
	global_store_dwordx4 v[148:149], v[144:147], off
.LBB0_210:
	s_or_b64 exec, exec, s[8:9]
	s_waitcnt vmcnt(15)
	v_lshlrev_b32_e32 v150, 16, v184
	v_and_b32_e32 v151, 0xffff0000, v184
	v_lshlrev_b32_e32 v228, 16, v186
	v_and_b32_e32 v229, 0xffff0000, v186
	v_lshlrev_b32_e32 v186, 16, v187
	v_and_b32_e32 v187, 0xffff0000, v187
	v_lshlrev_b32_e32 v184, 16, v185
	v_and_b32_e32 v185, 0xffff0000, v185
	v_pk_add_f32 v[140:141], v[140:141], v[150:151]
	v_pk_add_f32 v[150:151], v[138:139], v[186:187]
	v_pk_add_f32 v[138:139], v[136:137], v[228:229]
	v_pk_add_f32 v[142:143], v[142:143], v[184:185]
	v_cvt_pk_bf16_f32 v136, v140, v141
	s_nop 0
	v_cvt_pk_bf16_f32 v137, v142, v143
	v_cvt_pk_bf16_f32 v138, v138, v139
	v_cvt_pk_bf16_f32 v139, v150, v151
	s_and_saveexec_b64 s[8:9], vcc
	s_cbranch_execz .LBB0_212
	global_store_dwordx4 v[148:149], v[136:139], off offset:256

; __device__ __forceinline__ unsigned cvt_pk_bf16(float lo, float hi) { unsigned r; asm volatile("v_cvt_pk_bf16_f32 %0, %1, %2" : "=v"(r) : "v"(lo), "v"(hi)); return r; }
;     __device__ __forceinline__ void operator()(const f32x4 (&acc)[2][2][4][2], const Unit& u, int wr, int wc, int fr, int fq) const {
;     ...
;         for (int ai = 0; ai < 2; ++ai)
; #pragma unroll
;             for (int m = 0; m < 4; ++m) {
;                 const int r = r0 + ai * HALF + m * 16;
;                 const bool valid = r < NREAL + NMETA;
;                 float ssum = 0.f;
; #pragma unroll
;                 for (int bj = 0; bj < 2; ++bj) {
;                     const u32x4 hv = hold[ai][m][bj];
;                     f32x4 h0 = {__uint_as_float(hv.x << 16), __uint_as_float(hv.x & 0xffff0000u), __uint_as_float(hv.y << 16), __uint_as_float(hv.y & 0xffff0000u)};
;                     f32x4 h1 = {__uint_as_float(hv.z << 16), __uint_as_float(hv.z & 0xffff0000u), __uint_as_float(hv.w << 16), __uint_as_float(hv.w & 0xffff0000u)};
;                     h0 += acc[ai][bj][m][0]; h1 += acc[ai][bj][m][1];
;                     const int col0 = c0 + bj * HALF;
;                     u32x4 w; w.x = cvt_pk_bf16(h0[0], h0[1]); w.y = cvt_pk_bf16(h0[2], h0[3]); w.z = cvt_pk_bf16(h1[0], h1[1]); w.w = cvt_pk_bf16(h1[2], h1[3]);
;                     if (valid) *(u32x4*)(HB + (size_t)r * 2048 + col0) = w;
;                     h0 = (f32x4){__uint_as_float(w.x << 16), __uint_as_float(w.x & 0xffff0000u), __uint_as_float(w.y << 16), __uint_as_float(w.y & 0xffff0000u)};
;                     h1 = (f32x4){__uint_as_float(w.z << 16), __uint_as_float(w.z & 0xffff0000u), __uint_as_float(w.w << 16), __uint_as_float(w.w & 0xffff0000u)};
; #pragma unroll
;                     for (int j = 0; j < 4; ++j) ssum += h0[j] * h0[j] + h1[j] * h1[j];
;                 }
;                 ssum += __shfl_xor(ssum, 16); ssum += __shfl_xor(ssum, 32);
;                 if (fq == 0 && valid) atomicAdd(ssn + r, (unsigned long long)(ssum * 16777216.f));
.LBB0_214:
	s_or_b64 exec, exec, s[8:9]
	s_waitcnt vmcnt(16)
	v_lshlrev_b32_e32 v140, 16, v180
	s_waitcnt lgkmcnt(0)
	v_and_b32_e32 v141, 0xffff0000, v180
	v_lshlrev_b32_e32 v144, 16, v182
	v_and_b32_e32 v145, 0xffff0000, v182
	v_lshlrev_b32_e32 v146, 16, v183
	v_and_b32_e32 v147, 0xffff0000, v183
	v_pk_add_f32 v[124:125], v[124:125], v[140:141]
	v_pk_add_f32 v[140:141], v[122:123], v[146:147]
	v_pk_add_f32 v[122:123], v[120:121], v[144:145]
	v_cvt_pk_bf16_f32 v120, v124, v125
	v_lshl_add_u64 v[124:125], s[34:35], 0, v[220:221]
	v_cmp_gt_i32_e32 vcc, s84, v222
	v_lshlrev_b32_e32 v142, 16, v181
	v_and_b32_e32 v143, 0xffff0000, v181
	v_lshl_add_u64 v[124:125], v[200:201], 1, v[124:125]
	v_pk_add_f32 v[126:127], v[126:127], v[142:143]
	s_nop 0
	v_cvt_pk_bf16_f32 v121, v126, v127
	v_cvt_pk_bf16_f32 v122, v122, v123
	v_cvt_pk_bf16_f32 v123, v140, v141
	s_and_saveexec_b64 s[8:9], vcc
	s_cbranch_execz .LBB0_216
	global_store_dwordx4 v[124:125], v[120:123], off
.LBB0_216:
	s_or_b64 exec, exec, s[8:9]
	s_waitcnt vmcnt(16)
	v_lshlrev_b32_e32 v126, 16, v176
	v_and_b32_e32 v127, 0xffff0000, v176
	v_lshlrev_b32_e32 v142, 16, v178
	v_and_b32_e32 v143, 0xffff0000, v178
	v_lshlrev_b32_e32 v144, 16, v179
	v_and_b32_e32 v145, 0xffff0000, v179
	v_lshlrev_b32_e32 v140, 16, v177
	v_and_b32_e32 v141, 0xffff0000, v177
	v_pk_add_f32 v[116:117], v[116:117], v[126:127]
	v_pk_add_f32 v[126:127], v[114:115], v[144:145]
	v_pk_add_f32 v[114:115], v[112:113], v[142:143]
	v_pk_add_f32 v[118:119], v[118:119], v[140:141]
	v_cvt_pk_bf16_f32 v112, v116, v117
	s_nop 0
	v_cvt_pk_bf16_f32 v113, v118, v119
	v_cvt_pk_bf16_f32 v114, v114, v115
	v_cvt_pk_bf16_f32 v115, v126, v127
	s_and_saveexec_b64 s[8:9], vcc
	s_cbranch_execz .LBB0_218
	global_store_dwordx4 v[124:125], v[112:115], off offset:256

; __device__ __forceinline__ unsigned cvt_pk_bf16(float lo, float hi) { unsigned r; asm volatile("v_cvt_pk_bf16_f32 %0, %1, %2" : "=v"(r) : "v"(lo), "v"(hi)); return r; }
;     __device__ __forceinline__ void operator()(const f32x4 (&acc)[2][2][4][2], const Unit& u, int wr, int wc, int fr, int fq) const {
;     ...
;         for (int ai = 0; ai < 2; ++ai)
; #pragma unroll
;             for (int m = 0; m < 4; ++m) {
;                 const int r = r0 + ai * HALF + m * 16;
;                 const bool valid = r < NREAL + NMETA;
;                 float ssum = 0.f;
; #pragma unroll
;                 for (int bj = 0; bj < 2; ++bj) {
;                     const u32x4 hv = hold[ai][m][bj];
;                     f32x4 h0 = {__uint_as_float(hv.x << 16), __uint_as_float(hv.x & 0xffff0000u), __uint_as_float(hv.y << 16), __uint_as_float(hv.y & 0xffff0000u)};
;                     f32x4 h1 = {__uint_as_float(hv.z << 16), __uint_as_float(hv.z & 0xffff0000u), __uint_as_float(hv.w << 16), __uint_as_float(hv.w & 0xffff0000u)};
;                     h0 += acc[ai][bj][m][0]; h1 += acc[ai][bj][m][1];
;                     const int col0 = c0 + bj * HALF;
;                     u32x4 w; w.x = cvt_pk_bf16(h0[0], h0[1]); w.y = cvt_pk_bf16(h0[2], h0[3]); w.z = cvt_pk_bf16(h1[0], h1[1]); w.w = cvt_pk_bf16(h1[2], h1[3]);
;                     if (valid) *(u32x4*)(HB + (size_t)r * 2048 + col0) = w;
;                     h0 = (f32x4){__uint_as_float(w.x << 16), __uint_as_float(w.x & 0xffff0000u), __uint_as_float(w.y << 16), __uint_as_float(w.y & 0xffff0000u)};
;                     h1 = (f32x4){__uint_as_float(w.z << 16), __uint_as_float(w.z & 0xffff0000u), __uint_as_float(w.w << 16), __uint_as_float(w.w & 0xffff0000u)};
; #pragma unroll
;                     for (int j = 0; j < 4; ++j) ssum += h0[j] * h0[j] + h1[j] * h1[j];
;                 }
;                 ssum += __shfl_xor(ssum, 16); ssum += __shfl_xor(ssum, 32);
;                 if (fq == 0 && valid) atomicAdd(ssn + r, (unsigned long long)(ssum * 16777216.f));
.LBB0_220:
	s_or_b64 exec, exec, s[8:9]
	s_waitcnt vmcnt(17)
	v_lshlrev_b32_e32 v112, 16, v172
	s_waitcnt lgkmcnt(0)
	v_and_b32_e32 v113, 0xffff0000, v172
	v_lshlrev_b32_e32 v116, 16, v174
	v_and_b32_e32 v117, 0xffff0000, v174
	v_lshlrev_b32_e32 v118, 16, v175
	v_and_b32_e32 v119, 0xffff0000, v175
	v_pk_add_f32 v[100:101], v[100:101], v[112:113]
	v_pk_add_f32 v[112:113], v[98:99], v[118:119]
	v_pk_add_f32 v[98:99], v[96:97], v[116:117]
	v_cvt_pk_bf16_f32 v96, v100, v101
	v_lshl_add_u64 v[100:101], s[34:35], 0, v[216:217]
	v_cmp_gt_i32_e32 vcc, s84, v218
	v_lshlrev_b32_e32 v114, 16, v173
	v_and_b32_e32 v115, 0xffff0000, v173
	v_lshl_add_u64 v[100:101], v[200:201], 1, v[100:101]
	v_pk_add_f32 v[102:103], v[102:103], v[114:115]
	s_nop 0
	v_cvt_pk_bf16_f32 v97, v102, v103
	v_cvt_pk_bf16_f32 v98, v98, v99
	v_cvt_pk_bf16_f32 v99, v112, v113
	s_and_saveexec_b64 s[8:9], vcc
	s_cbranch_execz .LBB0_222
	global_store_dwordx4 v[100:101], v[96:99], off
.LBB0_222:
	s_or_b64 exec, exec, s[8:9]
	s_waitcnt vmcnt(17)
	v_lshlrev_b32_e32 v102, 16, v168
	v_and_b32_e32 v103, 0xffff0000, v168
	v_lshlrev_b32_e32 v114, 16, v170
	v_and_b32_e32 v115, 0xffff0000, v170
	v_lshlrev_b32_e32 v116, 16, v171
	v_and_b32_e32 v117, 0xffff0000, v171
	v_lshlrev_b32_e32 v112, 16, v169
	v_and_b32_e32 v113, 0xffff0000, v169
	v_pk_add_f32 v[92:93], v[92:93], v[102:103]
	v_pk_add_f32 v[102:103], v[86:87], v[116:117]
	v_pk_add_f32 v[86:87], v[84:85], v[114:115]
	v_pk_add_f32 v[94:95], v[94:95], v[112:113]
	v_cvt_pk_bf16_f32 v84, v92, v93
	s_nop 0
	v_cvt_pk_bf16_f32 v85, v94, v95
	v_cvt_pk_bf16_f32 v86, v86, v87
	v_cvt_pk_bf16_f32 v87, v102, v103
	s_and_saveexec_b64 s[8:9], vcc
	s_cbranch_execz .LBB0_224
	global_store_dwordx4 v[100:101], v[84:87], off offset:256

; __device__ __forceinline__ unsigned cvt_pk_bf16(float lo, float hi) { unsigned r; asm volatile("v_cvt_pk_bf16_f32 %0, %1, %2" : "=v"(r) : "v"(lo), "v"(hi)); return r; }
;     __device__ __forceinline__ void operator()(const f32x4 (&acc)[2][2][4][2], const Unit& u, int wr, int wc, int fr, int fq) const {
;     ...
;         for (int ai = 0; ai < 2; ++ai)
; #pragma unroll
;             for (int m = 0; m < 4; ++m) {
;                 const int r = r0 + ai * HALF + m * 16;
;                 const bool valid = r < NREAL + NMETA;
;                 float ssum = 0.f;
; #pragma unroll
;                 for (int bj = 0; bj < 2; ++bj) {
;                     const u32x4 hv = hold[ai][m][bj];
;                     f32x4 h0 = {__uint_as_float(hv.x << 16), __uint_as_float(hv.x & 0xffff0000u), __uint_as_float(hv.y << 16), __uint_as_float(hv.y & 0xffff0000u)};
;                     f32x4 h1 = {__uint_as_float(hv.z << 16), __uint_as_float(hv.z & 0xffff0000u), __uint_as_float(hv.w << 16), __uint_as_float(hv.w & 0xffff0000u)};
;                     h0 += acc[ai][bj][m][0]; h1 += acc[ai][bj][m][1];
;                     const int col0 = c0 + bj * HALF;
;                     u32x4 w; w.x = cvt_pk_bf16(h0[0], h0[1]); w.y = cvt_pk_bf16(h0[2], h0[3]); w.z = cvt_pk_bf16(h1[0], h1[1]); w.w = cvt_pk_bf16(h1[2], h1[3]);
;                     if (valid) *(u32x4*)(HB + (size_t)r * 2048 + col0) = w;
;                     h0 = (f32x4){__uint_as_float(w.x << 16), __uint_as_float(w.x & 0xffff0000u), __uint_as_float(w.y << 16), __uint_as_float(w.y & 0xffff0000u)};
;                     h1 = (f32x4){__uint_as_float(w.z << 16), __uint_as_float(w.z & 0xffff0000u), __uint_as_float(w.w << 16), __uint_as_float(w.w & 0xffff0000u)};
; #pragma unroll
;                     for (int j = 0; j < 4; ++j) ssum += h0[j] * h0[j] + h1[j] * h1[j];
;                 }
;                 ssum += __shfl_xor(ssum, 16); ssum += __shfl_xor(ssum, 32);
;                 if (fq == 0 && valid) atomicAdd(ssn + r, (unsigned long long)(ssum * 16777216.f));
.LBB0_226:
	s_or_b64 exec, exec, s[8:9]
	s_waitcnt vmcnt(18)
	v_lshlrev_b32_e32 v84, 16, v164
	s_waitcnt lgkmcnt(0)
	v_and_b32_e32 v85, 0xffff0000, v164
	v_lshlrev_b32_e32 v92, 16, v166
	v_and_b32_e32 v93, 0xffff0000, v166
	v_lshlrev_b32_e32 v94, 16, v167
	v_and_b32_e32 v95, 0xffff0000, v167
	v_pk_add_f32 v[76:77], v[76:77], v[84:85]
	v_pk_add_f32 v[84:85], v[74:75], v[94:95]
	v_pk_add_f32 v[74:75], v[72:73], v[92:93]
	v_cvt_pk_bf16_f32 v72, v76, v77
	v_lshl_add_u64 v[76:77], s[34:35], 0, v[212:213]
	v_cmp_gt_i32_e32 vcc, s84, v214
	v_lshlrev_b32_e32 v86, 16, v165
	v_and_b32_e32 v87, 0xffff0000, v165
	v_lshl_add_u64 v[76:77], v[200:201], 1, v[76:77]
	v_pk_add_f32 v[78:79], v[78:79], v[86:87]
	s_nop 0
	v_cvt_pk_bf16_f32 v73, v78, v79
	v_cvt_pk_bf16_f32 v74, v74, v75
	v_cvt_pk_bf16_f32 v75, v84, v85
	s_and_saveexec_b64 s[8:9], vcc
	s_cbranch_execz .LBB0_228
	global_store_dwordx4 v[76:77], v[72:75], off
.LBB0_228:
	s_or_b64 exec, exec, s[8:9]
	s_waitcnt vmcnt(18)
	v_lshlrev_b32_e32 v78, 16, v160
	v_and_b32_e32 v79, 0xffff0000, v160
	v_lshlrev_b32_e32 v86, 16, v162
	v_and_b32_e32 v87, 0xffff0000, v162
	v_lshlrev_b32_e32 v92, 16, v163
	v_and_b32_e32 v93, 0xffff0000, v163
	v_lshlrev_b32_e32 v84, 16, v161
	v_and_b32_e32 v85, 0xffff0000, v161
	v_pk_add_f32 v[68:69], v[68:69], v[78:79]
	v_pk_add_f32 v[78:79], v[66:67], v[92:93]
	v_pk_add_f32 v[66:67], v[64:65], v[86:87]
	v_pk_add_f32 v[70:71], v[70:71], v[84:85]
	v_cvt_pk_bf16_f32 v64, v68, v69
	s_nop 0
	v_cvt_pk_bf16_f32 v65, v70, v71
	v_cvt_pk_bf16_f32 v66, v66, v67
	v_cvt_pk_bf16_f32 v67, v78, v79
	s_and_saveexec_b64 s[8:9], vcc
	s_cbranch_execz .LBB0_230
	global_store_dwordx4 v[76:77], v[64:67], off offset:256

; __device__ __forceinline__ unsigned cvt_pk_bf16(float lo, float hi) { unsigned r; asm volatile("v_cvt_pk_bf16_f32 %0, %1, %2" : "=v"(r) : "v"(lo), "v"(hi)); return r; }
;     __device__ __forceinline__ void operator()(const f32x4 (&acc)[2][2][4][2], const Unit& u, int wr, int wc, int fr, int fq) const {
;     ...
;         for (int ai = 0; ai < 2; ++ai)
; #pragma unroll
;             for (int m = 0; m < 4; ++m) {
;                 const int r = r0 + ai * HALF + m * 16;
;                 const bool valid = r < NREAL + NMETA;
;                 float ssum = 0.f;
; #pragma unroll
;                 for (int bj = 0; bj < 2; ++bj) {
;                     const u32x4 hv = hold[ai][m][bj];
;                     f32x4 h0 = {__uint_as_float(hv.x << 16), __uint_as_float(hv.x & 0xffff0000u), __uint_as_float(hv.y << 16), __uint_as_float(hv.y & 0xffff0000u)};
;                     f32x4 h1 = {__uint_as_float(hv.z << 16), __uint_as_float(hv.z & 0xffff0000u), __uint_as_float(hv.w << 16), __uint_as_float(hv.w & 0xffff0000u)};
;                     h0 += acc[ai][bj][m][0]; h1 += acc[ai][bj][m][1];
;                     const int col0 = c0 + bj * HALF;
;                     u32x4 w; w.x = cvt_pk_bf16(h0[0], h0[1]); w.y = cvt_pk_bf16(h0[2], h0[3]); w.z = cvt_pk_bf16(h1[0], h1[1]); w.w = cvt_pk_bf16(h1[2], h1[3]);
;                     if (valid) *(u32x4*)(HB + (size_t)r * 2048 + col0) = w;
;                     h0 = (f32x4){__uint_as_float(w.x << 16), __uint_as_float(w.x & 0xffff0000u), __uint_as_float(w.y << 16), __uint_as_float(w.y & 0xffff0000u)};
;                     h1 = (f32x4){__uint_as_float(w.z << 16), __uint_as_float(w.z & 0xffff0000u), __uint_as_float(w.w << 16), __uint_as_float(w.w & 0xffff0000u)};
; #pragma unroll
;                     for (int j = 0; j < 4; ++j) ssum += h0[j] * h0[j] + h1[j] * h1[j];
;                 }
;                 ssum += __shfl_xor(ssum, 16); ssum += __shfl_xor(ssum, 32);
;                 if (fq == 0 && valid) atomicAdd(ssn + r, (unsigned long long)(ssum * 16777216.f));
.LBB0_232:
	s_or_b64 exec, exec, s[8:9]
	s_waitcnt vmcnt(19)
	v_lshlrev_b32_e32 v64, 16, v156
	s_waitcnt lgkmcnt(0)
	v_and_b32_e32 v65, 0xffff0000, v156
	v_lshlrev_b32_e32 v68, 16, v158
	v_and_b32_e32 v69, 0xffff0000, v158
	v_lshlrev_b32_e32 v70, 16, v159
	v_and_b32_e32 v71, 0xffff0000, v159
	v_pk_add_f32 v[60:61], v[60:61], v[64:65]
	s_movk_i32 s3, 0x6010
	v_pk_add_f32 v[64:65], v[58:59], v[70:71]
	v_pk_add_f32 v[58:59], v[56:57], v[68:69]
	v_cvt_pk_bf16_f32 v56, v60, v61
	v_lshl_add_u64 v[60:61], s[34:35], 0, v[210:211]
	v_cmp_gt_i32_e32 vcc, s3, v202
	v_lshlrev_b32_e32 v66, 16, v157
	v_and_b32_e32 v67, 0xffff0000, v157
	v_lshl_add_u64 v[60:61], v[200:201], 1, v[60:61]
	v_pk_add_f32 v[62:63], v[62:63], v[66:67]
	s_nop 0
	v_cvt_pk_bf16_f32 v57, v62, v63
	v_cvt_pk_bf16_f32 v58, v58, v59
	v_cvt_pk_bf16_f32 v59, v64, v65
	s_and_saveexec_b64 s[8:9], vcc
	s_cbranch_execz .LBB0_234
	global_store_dwordx4 v[60:61], v[56:59], off
.LBB0_234:
	s_or_b64 exec, exec, s[8:9]
	s_waitcnt vmcnt(19)
	v_lshlrev_b32_e32 v62, 16, v152
	v_and_b32_e32 v63, 0xffff0000, v152
	v_lshlrev_b32_e32 v66, 16, v154
	v_and_b32_e32 v67, 0xffff0000, v154
	v_lshlrev_b32_e32 v68, 16, v155
	v_and_b32_e32 v69, 0xffff0000, v155
	v_lshlrev_b32_e32 v64, 16, v153
	v_and_b32_e32 v65, 0xffff0000, v153
	v_pk_add_f32 v[52:53], v[52:53], v[62:63]
	v_pk_add_f32 v[62:63], v[50:51], v[68:69]
	v_pk_add_f32 v[50:51], v[48:49], v[66:67]
	v_pk_add_f32 v[54:55], v[54:55], v[64:65]
	v_cvt_pk_bf16_f32 v48, v52, v53
	s_nop 0
	v_cvt_pk_bf16_f32 v49, v54, v55
	v_cvt_pk_bf16_f32 v50, v50, v51
	v_cvt_pk_bf16_f32 v51, v62, v63
	s_and_saveexec_b64 s[8:9], vcc
	s_cbranch_execz .LBB0_236
	global_store_dwordx4 v[60:61], v[48:51], off offset:256

; __device__ __forceinline__ unsigned cvt_pk_bf16(float lo, float hi) { unsigned r; asm volatile("v_cvt_pk_bf16_f32 %0, %1, %2" : "=v"(r) : "v"(lo), "v"(hi)); return r; }
;     __device__ __forceinline__ void operator()(const f32x4 (&acc)[2][2][4][2], const Unit& u, int wr, int wc, int fr, int fq) const {
;     ...
;         for (int ai = 0; ai < 2; ++ai)
; #pragma unroll
;             for (int m = 0; m < 4; ++m) {
;                 const int r = r0 + ai * HALF + m * 16;
;                 const bool valid = r < NREAL + NMETA;
;                 float ssum = 0.f;
; #pragma unroll
;                 for (int bj = 0; bj < 2; ++bj) {
;                     const u32x4 hv = hold[ai][m][bj];
;                     f32x4 h0 = {__uint_as_float(hv.x << 16), __uint_as_float(hv.x & 0xffff0000u), __uint_as_float(hv.y << 16), __uint_as_float(hv.y & 0xffff0000u)};
;                     f32x4 h1 = {__uint_as_float(hv.z << 16), __uint_as_float(hv.z & 0xffff0000u), __uint_as_float(hv.w << 16), __uint_as_float(hv.w & 0xffff0000u)};
;                     h0 += acc[ai][bj][m][0]; h1 += acc[ai][bj][m][1];
;                     const int col0 = c0 + bj * HALF;
;                     u32x4 w; w.x = cvt_pk_bf16(h0[0], h0[1]); w.y = cvt_pk_bf16(h0[2], h0[3]); w.z = cvt_pk_bf16(h1[0], h1[1]); w.w = cvt_pk_bf16(h1[2], h1[3]);
;                     if (valid) *(u32x4*)(HB + (size_t)r * 2048 + col0) = w;
;                     h0 = (f32x4){__uint_as_float(w.x << 16), __uint_as_float(w.x & 0xffff0000u), __uint_as_float(w.y << 16), __uint_as_float(w.y & 0xffff0000u)};
;                     h1 = (f32x4){__uint_as_float(w.z << 16), __uint_as_float(w.z & 0xffff0000u), __uint_as_float(w.w << 16), __uint_as_float(w.w & 0xffff0000u)};
; #pragma unroll
;                     for (int j = 0; j < 4; ++j) ssum += h0[j] * h0[j] + h1[j] * h1[j];
;                 }
;                 ssum += __shfl_xor(ssum, 16); ssum += __shfl_xor(ssum, 32);
;                 if (fq == 0 && valid) atomicAdd(ssn + r, (unsigned long long)(ssum * 16777216.f));
.LBB0_238:
	s_or_b64 exec, exec, s[8:9]
	s_waitcnt vmcnt(20)
	v_lshlrev_b32_e32 v48, 16, v132
	s_waitcnt lgkmcnt(0)
	v_and_b32_e32 v49, 0xffff0000, v132
	v_lshlrev_b32_e32 v52, 16, v134
	v_and_b32_e32 v53, 0xffff0000, v134
	v_lshlrev_b32_e32 v54, 16, v135
	v_and_b32_e32 v55, 0xffff0000, v135
	v_pk_add_f32 v[44:45], v[44:45], v[48:49]
	v_pk_add_f32 v[48:49], v[42:43], v[54:55]
	v_pk_add_f32 v[42:43], v[40:41], v[52:53]
	v_cvt_pk_bf16_f32 v40, v44, v45
	v_lshl_add_u64 v[44:45], s[34:35], 0, v[208:209]
	v_cmp_gt_i32_e32 vcc, s43, v202
	v_lshlrev_b32_e32 v50, 16, v133
	v_and_b32_e32 v51, 0xffff0000, v133
	v_lshl_add_u64 v[44:45], v[200:201], 1, v[44:45]
	v_pk_add_f32 v[46:47], v[46:47], v[50:51]
	s_nop 0
	v_cvt_pk_bf16_f32 v41, v46, v47
	v_cvt_pk_bf16_f32 v42, v42, v43
	v_cvt_pk_bf16_f32 v43, v48, v49
	s_and_saveexec_b64 s[8:9], vcc
	s_cbranch_execz .LBB0_240
	global_store_dwordx4 v[44:45], v[40:43], off
.LBB0_240:
	s_or_b64 exec, exec, s[8:9]
	s_waitcnt vmcnt(20)
	v_lshlrev_b32_e32 v46, 16, v128
	v_and_b32_e32 v47, 0xffff0000, v128
	v_lshlrev_b32_e32 v50, 16, v130
	v_and_b32_e32 v51, 0xffff0000, v130
	v_lshlrev_b32_e32 v52, 16, v131
	v_and_b32_e32 v53, 0xffff0000, v131
	v_lshlrev_b32_e32 v48, 16, v129
	v_and_b32_e32 v49, 0xffff0000, v129
	v_pk_add_f32 v[36:37], v[36:37], v[46:47]
	v_pk_add_f32 v[46:47], v[34:35], v[52:53]
	v_pk_add_f32 v[34:35], v[32:33], v[50:51]
	v_pk_add_f32 v[38:39], v[38:39], v[48:49]
	v_cvt_pk_bf16_f32 v32, v36, v37
	s_nop 0
	v_cvt_pk_bf16_f32 v33, v38, v39
	v_cvt_pk_bf16_f32 v34, v34, v35
	v_cvt_pk_bf16_f32 v35, v46, v47
	s_and_saveexec_b64 s[8:9], vcc
	s_cbranch_execz .LBB0_242
	global_store_dwordx4 v[44:45], v[32:35], off offset:256

; __device__ __forceinline__ unsigned cvt_pk_bf16(float lo, float hi) { unsigned r; asm volatile("v_cvt_pk_bf16_f32 %0, %1, %2" : "=v"(r) : "v"(lo), "v"(hi)); return r; }
;     __device__ __forceinline__ void operator()(const f32x4 (&acc)[2][2][4][2], const Unit& u, int wr, int wc, int fr, int fq) const {
;     ...
;         for (int ai = 0; ai < 2; ++ai)
; #pragma unroll
;             for (int m = 0; m < 4; ++m) {
;                 const int r = r0 + ai * HALF + m * 16;
;                 const bool valid = r < NREAL + NMETA;
;                 float ssum = 0.f;
; #pragma unroll
;                 for (int bj = 0; bj < 2; ++bj) {
;                     const u32x4 hv = hold[ai][m][bj];
;                     f32x4 h0 = {__uint_as_float(hv.x << 16), __uint_as_float(hv.x & 0xffff0000u), __uint_as_float(hv.y << 16), __uint_as_float(hv.y & 0xffff0000u)};
;                     f32x4 h1 = {__uint_as_float(hv.z << 16), __uint_as_float(hv.z & 0xffff0000u), __uint_as_float(hv.w << 16), __uint_as_float(hv.w & 0xffff0000u)};
;                     h0 += acc[ai][bj][m][0]; h1 += acc[ai][bj][m][1];
;                     const int col0 = c0 + bj * HALF;
;                     u32x4 w; w.x = cvt_pk_bf16(h0[0], h0[1]); w.y = cvt_pk_bf16(h0[2], h0[3]); w.z = cvt_pk_bf16(h1[0], h1[1]); w.w = cvt_pk_bf16(h1[2], h1[3]);
;                     if (valid) *(u32x4*)(HB + (size_t)r * 2048 + col0) = w;
;                     h0 = (f32x4){__uint_as_float(w.x << 16), __uint_as_float(w.x & 0xffff0000u), __uint_as_float(w.y << 16), __uint_as_float(w.y & 0xffff0000u)};
;                     h1 = (f32x4){__uint_as_float(w.z << 16), __uint_as_float(w.z & 0xffff0000u), __uint_as_float(w.w << 16), __uint_as_float(w.w & 0xffff0000u)};
; #pragma unroll
;                     for (int j = 0; j < 4; ++j) ssum += h0[j] * h0[j] + h1[j] * h1[j];
;                 }
;                 ssum += __shfl_xor(ssum, 16); ssum += __shfl_xor(ssum, 32);
;                 if (fq == 0 && valid) atomicAdd(ssn + r, (unsigned long long)(ssum * 16777216.f));
.LBB0_244:
	s_or_b64 exec, exec, s[8:9]
	s_waitcnt vmcnt(21)
	v_lshlrev_b32_e32 v32, 16, v108
	s_waitcnt lgkmcnt(0)
	v_and_b32_e32 v33, 0xffff0000, v108
	v_lshlrev_b32_e32 v36, 16, v110
	v_and_b32_e32 v37, 0xffff0000, v110
	v_lshlrev_b32_e32 v38, 16, v111
	v_and_b32_e32 v39, 0xffff0000, v111
	v_pk_add_f32 v[28:29], v[28:29], v[32:33]
	s_movk_i32 s3, 0x5ff0
	v_pk_add_f32 v[32:33], v[26:27], v[38:39]
	v_pk_add_f32 v[26:27], v[24:25], v[36:37]
	v_cvt_pk_bf16_f32 v24, v28, v29
	v_lshl_add_u64 v[28:29], s[34:35], 0, v[206:207]
	v_cmp_gt_i32_e32 vcc, s3, v202
	v_lshlrev_b32_e32 v34, 16, v109
	v_and_b32_e32 v35, 0xffff0000, v109
	v_lshl_add_u64 v[28:29], v[200:201], 1, v[28:29]
	v_pk_add_f32 v[30:31], v[30:31], v[34:35]
	s_nop 0
	v_cvt_pk_bf16_f32 v25, v30, v31
	v_cvt_pk_bf16_f32 v26, v26, v27
	v_cvt_pk_bf16_f32 v27, v32, v33
	s_and_saveexec_b64 s[8:9], vcc
	s_cbranch_execz .LBB0_246
	global_store_dwordx4 v[28:29], v[24:27], off
.LBB0_246:
	s_or_b64 exec, exec, s[8:9]
	s_waitcnt vmcnt(21)
	v_lshlrev_b32_e32 v30, 16, v104
	v_and_b32_e32 v31, 0xffff0000, v104
	v_lshlrev_b32_e32 v34, 16, v106
	v_and_b32_e32 v35, 0xffff0000, v106
	v_lshlrev_b32_e32 v36, 16, v107
	v_and_b32_e32 v37, 0xffff0000, v107
	v_lshlrev_b32_e32 v32, 16, v105
	v_and_b32_e32 v33, 0xffff0000, v105
	v_pk_add_f32 v[20:21], v[20:21], v[30:31]
	v_pk_add_f32 v[30:31], v[18:19], v[36:37]
	v_pk_add_f32 v[18:19], v[16:17], v[34:35]
	v_pk_add_f32 v[22:23], v[22:23], v[32:33]
	v_cvt_pk_bf16_f32 v16, v20, v21
	s_nop 0
	v_cvt_pk_bf16_f32 v17, v22, v23
	v_cvt_pk_bf16_f32 v18, v18, v19
	v_cvt_pk_bf16_f32 v19, v30, v31
	s_and_saveexec_b64 s[8:9], vcc
	s_cbranch_execz .LBB0_248
	global_store_dwordx4 v[28:29], v[16:19], off offset:256

; __device__ __forceinline__ unsigned cvt_pk_bf16(float lo, float hi) { unsigned r; asm volatile("v_cvt_pk_bf16_f32 %0, %1, %2" : "=v"(r) : "v"(lo), "v"(hi)); return r; }
;     __device__ __forceinline__ void operator()(const f32x4 (&acc)[2][2][4][2], const Unit& u, int wr, int wc, int fr, int fq) const {
;     ...
;         for (int ai = 0; ai < 2; ++ai)
; #pragma unroll
;             for (int m = 0; m < 4; ++m) {
;                 const int r = r0 + ai * HALF + m * 16;
;                 const bool valid = r < NREAL + NMETA;
;                 float ssum = 0.f;
; #pragma unroll
;                 for (int bj = 0; bj < 2; ++bj) {
;                     const u32x4 hv = hold[ai][m][bj];
;                     f32x4 h0 = {__uint_as_float(hv.x << 16), __uint_as_float(hv.x & 0xffff0000u), __uint_as_float(hv.y << 16), __uint_as_float(hv.y & 0xffff0000u)};
;                     f32x4 h1 = {__uint_as_float(hv.z << 16), __uint_as_float(hv.z & 0xffff0000u), __uint_as_float(hv.w << 16), __uint_as_float(hv.w & 0xffff0000u)};
;                     h0 += acc[ai][bj][m][0]; h1 += acc[ai][bj][m][1];
;                     const int col0 = c0 + bj * HALF;
;                     u32x4 w; w.x = cvt_pk_bf16(h0[0], h0[1]); w.y = cvt_pk_bf16(h0[2], h0[3]); w.z = cvt_pk_bf16(h1[0], h1[1]); w.w = cvt_pk_bf16(h1[2], h1[3]);
;                     if (valid) *(u32x4*)(HB + (size_t)r * 2048 + col0) = w;
;                     h0 = (f32x4){__uint_as_float(w.x << 16), __uint_as_float(w.x & 0xffff0000u), __uint_as_float(w.y << 16), __uint_as_float(w.y & 0xffff0000u)};
;                     h1 = (f32x4){__uint_as_float(w.z << 16), __uint_as_float(w.z & 0xffff0000u), __uint_as_float(w.w << 16), __uint_as_float(w.w & 0xffff0000u)};
; #pragma unroll
;                     for (int j = 0; j < 4; ++j) ssum += h0[j] * h0[j] + h1[j] * h1[j];
;                 }
;                 ssum += __shfl_xor(ssum, 16); ssum += __shfl_xor(ssum, 32);
;                 if (fq == 0 && valid) atomicAdd(ssn + r, (unsigned long long)(ssum * 16777216.f));
.LBB0_250:
	s_or_b64 exec, exec, s[8:9]
	s_waitcnt vmcnt(22)
	v_lshlrev_b32_e32 v16, 16, v88
	s_waitcnt lgkmcnt(0)
	v_and_b32_e32 v17, 0xffff0000, v88
	v_lshlrev_b32_e32 v20, 16, v90
	v_and_b32_e32 v21, 0xffff0000, v90
	v_lshlrev_b32_e32 v22, 16, v91
	v_and_b32_e32 v23, 0xffff0000, v91
	v_pk_add_f32 v[12:13], v[12:13], v[16:17]
	s_movk_i32 s3, 0x5fe0
	v_pk_add_f32 v[16:17], v[10:11], v[22:23]
	v_pk_add_f32 v[10:11], v[8:9], v[20:21]
	v_cvt_pk_bf16_f32 v8, v12, v13
	v_lshl_add_u64 v[12:13], s[34:35], 0, v[204:205]
	v_cmp_gt_i32_e32 vcc, s3, v202
	v_lshlrev_b32_e32 v18, 16, v89
	v_and_b32_e32 v19, 0xffff0000, v89
	v_lshl_add_u64 v[12:13], v[200:201], 1, v[12:13]
	v_pk_add_f32 v[14:15], v[14:15], v[18:19]
	s_nop 0
	v_cvt_pk_bf16_f32 v9, v14, v15
	v_cvt_pk_bf16_f32 v10, v10, v11
	v_cvt_pk_bf16_f32 v11, v16, v17
	s_and_saveexec_b64 s[8:9], vcc
	s_cbranch_execz .LBB0_252
	global_store_dwordx4 v[12:13], v[8:11], off
.LBB0_252:
	s_or_b64 exec, exec, s[8:9]
	s_waitcnt vmcnt(22)
	v_lshlrev_b32_e32 v14, 16, v80
	v_and_b32_e32 v15, 0xffff0000, v80
	v_lshlrev_b32_e32 v18, 16, v82
	v_and_b32_e32 v19, 0xffff0000, v82
	v_lshlrev_b32_e32 v20, 16, v83
	v_and_b32_e32 v21, 0xffff0000, v83
	v_lshlrev_b32_e32 v16, 16, v81
	v_and_b32_e32 v17, 0xffff0000, v81
	v_pk_add_f32 v[4:5], v[4:5], v[14:15]
	v_pk_add_f32 v[14:15], v[2:3], v[20:21]
	v_pk_add_f32 v[2:3], v[0:1], v[18:19]
	v_pk_add_f32 v[6:7], v[6:7], v[16:17]
	v_cvt_pk_bf16_f32 v0, v4, v5
	s_nop 0
	v_cvt_pk_bf16_f32 v1, v6, v7
	v_cvt_pk_bf16_f32 v2, v2, v3
	v_cvt_pk_bf16_f32 v3, v14, v15
	s_and_saveexec_b64 s[8:9], vcc
	s_cbranch_execz .LBB0_254
	global_store_dwordx4 v[12:13], v[0:3], off offset:256
